# GEMM k-step (gres1, gres2, kvq): first fragment reads of each half issued before the global-load block
# speedup vs baseline: 1.0262x; 1.0036x over previous
.LBB0_884:
	s_cmp_lt_u32 s39, 14
	s_cselect_b64 s[8:9], -1, 0
	s_cmp_gt_u32 s39, 13
	s_cselect_b64 s[6:7], -1, 0
	s_and_b64 vcc, exec, s[6:7]
	v_lshl_add_u64 v[136:137], v[132:133], 0, v[128:129]
	v_lshl_add_u64 v[134:135], v[130:131], 0, v[128:129]
	v_add_u32_e32 v151, v142, v143
	ds_read_b128 v[154:157], v151
	v_add_u32_e32 v152, v142, v145
	ds_read_b128 v[158:161], v152 offset:16384
	ds_read_b128 v[162:165], v151 offset:4096
	ds_read_b128 v[166:169], v152 offset:20480
	s_cbranch_vccnz .LBB0_886
	s_waitcnt vmcnt(8)
	v_add_co_u32_e32 v80, vcc, 0x10000, v136
	global_load_dwordx4 v[64:67], v[136:137], off offset:256
	global_load_dwordx4 v[72:75], v[134:135], off offset:256
	v_addc_co_u32_e32 v81, vcc, 0, v137, vcc
	v_add_co_u32_e32 v88, vcc, 0x10000, v134
	global_load_dwordx4 v[80:83], v[80:81], off offset:256
	s_nop 0
	v_addc_co_u32_e32 v89, vcc, 0, v135, vcc
	v_add_co_u32_e32 v96, vcc, 0x20000, v136
	global_load_dwordx4 v[88:91], v[88:89], off offset:256
	s_nop 0
	v_addc_co_u32_e32 v97, vcc, 0, v137, vcc
	v_add_co_u32_e32 v104, vcc, 0x20000, v134
	global_load_dwordx4 v[96:99], v[96:97], off offset:256
	s_nop 0
	v_addc_co_u32_e32 v105, vcc, 0, v135, vcc
	v_add_co_u32_e32 v112, vcc, 0x30000, v136
	global_load_dwordx4 v[104:107], v[104:105], off offset:256
	s_nop 0
	v_addc_co_u32_e32 v113, vcc, 0, v137, vcc
	v_add_co_u32_e32 v120, vcc, 0x30000, v134
	global_load_dwordx4 v[112:115], v[112:113], off offset:256
	s_nop 0
	v_addc_co_u32_e32 v121, vcc, 0, v135, vcc
	global_load_dwordx4 v[120:123], v[120:121], off offset:256

.Lg1w_w1:
	ds_write_b128 v141, v[68:71] offset:32768
	ds_write_b128 v141, v[76:79] offset:49152
	v_add_u32_e32 v153, v148, v143
	s_waitcnt lgkmcnt(2)
	v_mfma_f32_32x32x16_bf16 v[16:31], v[162:165], v[158:161], v[16:31]
	s_cmp_gt_u32 s39, 12
	v_mfma_f32_32x32x16_bf16 v[48:63], v[154:157], v[158:161], v[48:63]
	v_mfma_f32_32x32x16_bf16 v[32:47], v[154:157], v[166:169], v[32:47]
	ds_read_b128 v[156:159], v153
	v_add_u32_e32 v154, v148, v145
	v_add_u32_e32 v155, v149, v143
	v_mfma_f32_32x32x16_bf16 v[0:15], v[162:165], v[166:169], v[0:15]
	ds_read_b128 v[160:163], v154 offset:16384
	ds_read_b128 v[164:167], v153 offset:4096
	ds_read_b128 v[168:171], v154 offset:20480
	ds_write_b128 v141, v[84:87] offset:36864
	ds_write_b128 v141, v[92:95] offset:53248
	s_waitcnt lgkmcnt(2)
	v_mfma_f32_32x32x16_bf16 v[48:63], v[156:159], v[160:163], v[48:63]
	v_mfma_f32_32x32x16_bf16 v[32:47], v[156:159], v[168:171], v[32:47]
	v_add_u32_e32 v156, v149, v145
	v_add_u32_e32 v157, v150, v143
	v_mfma_f32_32x32x16_bf16 v[16:31], v[164:167], v[160:163], v[16:31]
	ds_read_b128 v[158:161], v155
	v_mfma_f32_32x32x16_bf16 v[0:15], v[164:167], v[168:171], v[0:15]
	ds_read_b128 v[162:165], v156 offset:16384
	ds_read_b128 v[166:169], v155 offset:4096
	ds_read_b128 v[170:173], v156 offset:20480
	ds_write_b128 v141, v[100:103] offset:40960
	ds_write_b128 v141, v[108:111] offset:57344
	s_waitcnt lgkmcnt(2)
	v_mfma_f32_32x32x16_bf16 v[48:63], v[158:161], v[162:165], v[48:63]
	v_mfma_f32_32x32x16_bf16 v[32:47], v[158:161], v[170:173], v[32:47]
	v_add_u32_e32 v158, v150, v145
	v_mfma_f32_32x32x16_bf16 v[16:31], v[166:169], v[162:165], v[16:31]
	ds_read_b128 v[160:163], v157
	v_mfma_f32_32x32x16_bf16 v[0:15], v[166:169], v[170:173], v[0:15]
	ds_read_b128 v[164:167], v158 offset:16384
	ds_read_b128 v[168:171], v157 offset:4096
	ds_read_b128 v[172:175], v158 offset:20480
	ds_write_b128 v141, v[116:119] offset:45056
	ds_write_b128 v141, v[124:127] offset:61440
	s_waitcnt lgkmcnt(2)
	v_mfma_f32_32x32x16_bf16 v[48:63], v[160:163], v[164:167], v[48:63]
	v_mfma_f32_32x32x16_bf16 v[32:47], v[160:163], v[172:175], v[32:47]
	v_mfma_f32_32x32x16_bf16 v[16:31], v[168:171], v[164:167], v[16:31]
	v_mfma_f32_32x32x16_bf16 v[0:15], v[168:171], v[172:175], v[0:15]
	s_waitcnt lgkmcnt(0)
	s_barrier
	ds_read_b128 v[160:163], v152 offset:49152
	ds_read_b128 v[164:167], v151 offset:36864
	ds_read_b128 v[168:171], v152 offset:53248
	s_cbranch_scc1 .LBB0_888
	v_add_co_u32_e32 v84, vcc, 0x10000, v136
	global_load_dwordx4 v[68:71], v[136:137], off offset:384
	global_load_dwordx4 v[76:79], v[134:135], off offset:384
	v_addc_co_u32_e32 v85, vcc, 0, v137, vcc
	v_add_co_u32_e32 v92, vcc, 0x10000, v134
	global_load_dwordx4 v[84:87], v[84:85], off offset:384
	s_nop 0
	v_addc_co_u32_e32 v93, vcc, 0, v135, vcc
	v_add_co_u32_e32 v100, vcc, 0x20000, v136
	global_load_dwordx4 v[92:95], v[92:93], off offset:384
	s_nop 0
	v_addc_co_u32_e32 v101, vcc, 0, v137, vcc
	v_add_co_u32_e32 v108, vcc, 0x20000, v134
	global_load_dwordx4 v[100:103], v[100:101], off offset:384
	s_nop 0
	v_addc_co_u32_e32 v109, vcc, 0, v135, vcc
	v_add_co_u32_e32 v116, vcc, 0x30000, v136
	global_load_dwordx4 v[108:111], v[108:109], off offset:384
	s_nop 0
	v_addc_co_u32_e32 v117, vcc, 0, v137, vcc
	v_add_co_u32_e32 v124, vcc, 0x30000, v134
	global_load_dwordx4 v[116:119], v[116:117], off offset:384
	s_nop 0
	v_addc_co_u32_e32 v125, vcc, 0, v135, vcc
	global_load_dwordx4 v[124:127], v[124:125], off offset:384
.LBB0_888:
	s_waitcnt vmcnt(8)
	ds_read_b128 v[134:137], v151 offset:32768
	ds_write_b128 v141, v[64:67]
	ds_write_b128 v141, v[72:75] offset:16384
	s_andn2_b64 vcc, exec, s[8:9]
	s_waitcnt lgkmcnt(2)
	v_mfma_f32_32x32x16_bf16 v[48:63], v[134:137], v[160:163], v[48:63]
	v_mfma_f32_32x32x16_bf16 v[32:47], v[134:137], v[168:171], v[32:47]
	v_mfma_f32_32x32x16_bf16 v[16:31], v[164:167], v[160:163], v[16:31]
	v_mfma_f32_32x32x16_bf16 v[0:15], v[164:167], v[168:171], v[0:15]
	ds_read_b128 v[134:137], v153 offset:32768
	ds_read_b128 v[160:163], v154 offset:49152
	ds_read_b128 v[164:167], v153 offset:36864
	ds_read_b128 v[168:171], v154 offset:53248
	ds_write_b128 v141, v[80:83] offset:4096
	ds_write_b128 v141, v[88:91] offset:20480
	s_waitcnt lgkmcnt(2)
	v_mfma_f32_32x32x16_bf16 v[48:63], v[134:137], v[160:163], v[48:63]
	v_mfma_f32_32x32x16_bf16 v[32:47], v[134:137], v[168:171], v[32:47]
	v_mfma_f32_32x32x16_bf16 v[16:31], v[164:167], v[160:163], v[16:31]
	v_mfma_f32_32x32x16_bf16 v[0:15], v[164:167], v[168:171], v[0:15]
	ds_read_b128 v[134:137], v155 offset:32768
	ds_read_b128 v[160:163], v156 offset:49152
	ds_read_b128 v[152:155], v155 offset:36864
	ds_read_b128 v[164:167], v156 offset:53248
	ds_write_b128 v141, v[96:99] offset:8192
	ds_write_b128 v141, v[104:107] offset:24576
	s_waitcnt lgkmcnt(2)
	v_mfma_f32_32x32x16_bf16 v[48:63], v[134:137], v[160:163], v[48:63]
	v_mfma_f32_32x32x16_bf16 v[32:47], v[134:137], v[164:167], v[32:47]
	v_mfma_f32_32x32x16_bf16 v[16:31], v[152:155], v[160:163], v[16:31]
	v_mfma_f32_32x32x16_bf16 v[0:15], v[152:155], v[164:167], v[0:15]
	ds_read_b128 v[134:137], v157 offset:32768
	ds_read_b128 v[152:155], v158 offset:49152
	ds_read_b128 v[160:163], v157 offset:36864
	ds_read_b128 v[156:159], v158 offset:53248
	ds_write_b128 v141, v[112:115] offset:12288
	ds_write_b128 v141, v[120:123] offset:28672
	s_waitcnt lgkmcnt(2)
	v_mfma_f32_32x32x16_bf16 v[48:63], v[134:137], v[152:155], v[48:63]
	v_mfma_f32_32x32x16_bf16 v[32:47], v[134:137], v[156:159], v[32:47]
	v_mfma_f32_32x32x16_bf16 v[16:31], v[160:163], v[152:155], v[16:31]
	v_mfma_f32_32x32x16_bf16 v[0:15], v[160:163], v[156:159], v[0:15]
	s_branch .LBB0_883

.LBB0_1008:
	s_cmp_lt_u32 s68, 14
	s_cselect_b64 s[8:9], -1, 0
	s_cmp_gt_u32 s68, 13
	s_cselect_b64 s[0:1], -1, 0
	s_and_b64 vcc, exec, s[0:1]
	v_lshl_add_u64 v[194:195], v[190:191], 0, v[130:131]
	v_lshl_add_u64 v[192:193], v[188:189], 0, v[130:131]
	v_add_u32_e32 v153, v137, v139
	ds_read_b128 v[218:221], v153
	v_add_u32_e32 v155, v137, v141
	ds_read_b128 v[222:225], v155 offset:16384
	ds_read_b128 v[226:229], v153 offset:4096
	ds_read_b128 v[230:233], v155 offset:20480
	s_cbranch_vccnz .LBB0_1010
	s_waitcnt vmcnt(8)
	v_add_co_u32_e32 v80, vcc, 0x10000, v194
	global_load_dwordx4 v[64:67], v[194:195], off offset:256
	global_load_dwordx4 v[72:75], v[192:193], off offset:256
	v_addc_co_u32_e32 v81, vcc, 0, v195, vcc
	v_add_co_u32_e32 v88, vcc, 0x10000, v192
	global_load_dwordx4 v[80:83], v[80:81], off offset:256
	s_nop 0
	v_addc_co_u32_e32 v89, vcc, 0, v193, vcc
	v_add_co_u32_e32 v96, vcc, 0x20000, v194
	global_load_dwordx4 v[88:91], v[88:89], off offset:256
	s_nop 0
	v_addc_co_u32_e32 v97, vcc, 0, v195, vcc
	v_add_co_u32_e32 v104, vcc, 0x20000, v192
	global_load_dwordx4 v[96:99], v[96:97], off offset:256
	s_nop 0
	v_addc_co_u32_e32 v105, vcc, 0, v193, vcc
	v_add_co_u32_e32 v112, vcc, 0x30000, v194
	global_load_dwordx4 v[104:107], v[104:105], off offset:256
	s_nop 0
	v_addc_co_u32_e32 v113, vcc, 0, v195, vcc
	v_add_co_u32_e32 v120, vcc, 0x30000, v192
	global_load_dwordx4 v[112:115], v[112:113], off offset:256
	s_nop 0
	v_addc_co_u32_e32 v121, vcc, 0, v193, vcc
	global_load_dwordx4 v[120:123], v[120:121], off offset:256

.Lkqw_w1:
	ds_write_b128 v135, v[68:71] offset:32768
	ds_write_b128 v135, v[76:79] offset:49152
	v_add_u32_e32 v157, v143, v139
	s_waitcnt lgkmcnt(2)
	v_mfma_f32_32x32x16_bf16 v[0:15], v[226:229], v[222:225], v[0:15]
	v_add_u32_e32 v159, v143, v141
	v_add_u32_e32 v161, v149, v139
	v_add_u32_e32 v163, v149, v141
	v_add_u32_e32 v165, v151, v139
	v_add_u32_e32 v167, v151, v141
	s_cmp_gt_u32 s68, 12
	v_mfma_f32_32x32x16_bf16 v[32:47], v[218:221], v[222:225], v[32:47]
	v_mfma_f32_32x32x16_bf16 v[48:63], v[218:221], v[230:233], v[48:63]
	ds_read_b128 v[218:221], v157
	v_mfma_f32_32x32x16_bf16 v[16:31], v[226:229], v[230:233], v[16:31]
	ds_read_b128 v[222:225], v159 offset:16384
	ds_read_b128 v[226:229], v157 offset:4096
	ds_read_b128 v[230:233], v159 offset:20480
	ds_write_b128 v135, v[84:87] offset:36864
	ds_write_b128 v135, v[92:95] offset:53248
	s_waitcnt lgkmcnt(2)
	v_mfma_f32_32x32x16_bf16 v[32:47], v[218:221], v[222:225], v[32:47]
	v_mfma_f32_32x32x16_bf16 v[48:63], v[218:221], v[230:233], v[48:63]
	ds_read_b128 v[218:221], v161
	v_mfma_f32_32x32x16_bf16 v[0:15], v[226:229], v[222:225], v[0:15]
	v_mfma_f32_32x32x16_bf16 v[16:31], v[226:229], v[230:233], v[16:31]
	ds_read_b128 v[222:225], v163 offset:16384
	ds_read_b128 v[226:229], v161 offset:4096
	ds_read_b128 v[230:233], v163 offset:20480
	ds_write_b128 v135, v[100:103] offset:40960
	ds_write_b128 v135, v[108:111] offset:57344
	s_waitcnt lgkmcnt(2)
	v_mfma_f32_32x32x16_bf16 v[32:47], v[218:221], v[222:225], v[32:47]
	v_mfma_f32_32x32x16_bf16 v[48:63], v[218:221], v[230:233], v[48:63]
	ds_read_b128 v[218:221], v165
	v_mfma_f32_32x32x16_bf16 v[0:15], v[226:229], v[222:225], v[0:15]
	v_mfma_f32_32x32x16_bf16 v[16:31], v[226:229], v[230:233], v[16:31]
	ds_read_b128 v[222:225], v167 offset:16384
	ds_read_b128 v[226:229], v165 offset:4096
	ds_read_b128 v[230:233], v167 offset:20480
	ds_write_b128 v135, v[116:119] offset:45056
	ds_write_b128 v135, v[124:127] offset:61440
	s_waitcnt lgkmcnt(2)
	v_mfma_f32_32x32x16_bf16 v[32:47], v[218:221], v[222:225], v[32:47]
	v_mfma_f32_32x32x16_bf16 v[48:63], v[218:221], v[230:233], v[48:63]
	v_mfma_f32_32x32x16_bf16 v[0:15], v[226:229], v[222:225], v[0:15]
	v_mfma_f32_32x32x16_bf16 v[16:31], v[226:229], v[230:233], v[16:31]
	s_waitcnt lgkmcnt(0)
	s_barrier
	ds_read_b128 v[218:221], v155 offset:49152
	ds_read_b128 v[222:225], v153 offset:36864
	ds_read_b128 v[226:229], v155 offset:53248
	s_cbranch_scc1 .LBB0_1012
	v_add_co_u32_e32 v84, vcc, 0x10000, v194
	global_load_dwordx4 v[68:71], v[194:195], off offset:384
	global_load_dwordx4 v[76:79], v[192:193], off offset:384
	v_addc_co_u32_e32 v85, vcc, 0, v195, vcc
	v_add_co_u32_e32 v92, vcc, 0x10000, v192
	global_load_dwordx4 v[84:87], v[84:85], off offset:384
	s_nop 0
	v_addc_co_u32_e32 v93, vcc, 0, v193, vcc
	v_add_co_u32_e32 v100, vcc, 0x20000, v194
	global_load_dwordx4 v[92:95], v[92:93], off offset:384
	s_nop 0
	v_addc_co_u32_e32 v101, vcc, 0, v195, vcc
	v_add_co_u32_e32 v108, vcc, 0x20000, v192
	global_load_dwordx4 v[100:103], v[100:101], off offset:384
	s_nop 0
	v_addc_co_u32_e32 v109, vcc, 0, v193, vcc
	v_add_co_u32_e32 v116, vcc, 0x30000, v194
	global_load_dwordx4 v[108:111], v[108:109], off offset:384
	s_nop 0
	v_addc_co_u32_e32 v117, vcc, 0, v195, vcc
	v_add_co_u32_e32 v124, vcc, 0x30000, v192
	global_load_dwordx4 v[116:119], v[116:117], off offset:384
	s_nop 0
	v_addc_co_u32_e32 v125, vcc, 0, v193, vcc
	global_load_dwordx4 v[124:127], v[124:125], off offset:384
.LBB0_1012:
	s_waitcnt vmcnt(8)
	ds_read_b128 v[192:195], v153 offset:32768
	ds_write_b128 v135, v[64:67]
	ds_write_b128 v135, v[72:75] offset:16384
	s_andn2_b64 vcc, exec, s[8:9]
	s_waitcnt lgkmcnt(2)
	v_mfma_f32_32x32x16_bf16 v[32:47], v[192:195], v[218:221], v[32:47]
	v_mfma_f32_32x32x16_bf16 v[48:63], v[192:195], v[226:229], v[48:63]
	v_mfma_f32_32x32x16_bf16 v[0:15], v[222:225], v[218:221], v[0:15]
	v_mfma_f32_32x32x16_bf16 v[16:31], v[222:225], v[226:229], v[16:31]
	ds_read_b128 v[192:195], v157 offset:32768
	ds_read_b128 v[218:221], v159 offset:49152
	ds_read_b128 v[222:225], v157 offset:36864
	ds_read_b128 v[226:229], v159 offset:53248
	ds_write_b128 v135, v[80:83] offset:4096
	ds_write_b128 v135, v[88:91] offset:20480
	s_waitcnt lgkmcnt(2)
	v_mfma_f32_32x32x16_bf16 v[32:47], v[192:195], v[218:221], v[32:47]
	v_mfma_f32_32x32x16_bf16 v[48:63], v[192:195], v[226:229], v[48:63]
	v_mfma_f32_32x32x16_bf16 v[0:15], v[222:225], v[218:221], v[0:15]
	v_mfma_f32_32x32x16_bf16 v[16:31], v[222:225], v[226:229], v[16:31]
	ds_read_b128 v[192:195], v161 offset:32768
	ds_read_b128 v[218:221], v163 offset:49152
	ds_read_b128 v[222:225], v161 offset:36864
	ds_read_b128 v[226:229], v163 offset:53248
	ds_write_b128 v135, v[96:99] offset:8192
	ds_write_b128 v135, v[104:107] offset:24576
	s_waitcnt lgkmcnt(2)
	v_mfma_f32_32x32x16_bf16 v[32:47], v[192:195], v[218:221], v[32:47]
	v_mfma_f32_32x32x16_bf16 v[48:63], v[192:195], v[226:229], v[48:63]
	v_mfma_f32_32x32x16_bf16 v[0:15], v[222:225], v[218:221], v[0:15]
	v_mfma_f32_32x32x16_bf16 v[16:31], v[222:225], v[226:229], v[16:31]
	ds_read_b128 v[192:195], v165 offset:32768
	ds_read_b128 v[218:221], v167 offset:49152
	ds_read_b128 v[222:225], v165 offset:36864
	ds_read_b128 v[226:229], v167 offset:53248
	ds_write_b128 v135, v[112:115] offset:12288
	ds_write_b128 v135, v[120:123] offset:28672
	s_waitcnt lgkmcnt(2)
	v_mfma_f32_32x32x16_bf16 v[32:47], v[192:195], v[218:221], v[32:47]
	v_mfma_f32_32x32x16_bf16 v[48:63], v[192:195], v[226:229], v[48:63]
	v_mfma_f32_32x32x16_bf16 v[0:15], v[222:225], v[218:221], v[0:15]
	v_mfma_f32_32x32x16_bf16 v[16:31], v[222:225], v[226:229], v[16:31]
	s_branch .LBB0_1007

.LBB0_1506:
	s_cmp_lt_u32 s16, 14
	s_cselect_b64 s[6:7], -1, 0
	s_cmp_gt_u32 s16, 13
	s_cselect_b64 s[4:5], -1, 0
	s_and_b64 vcc, exec, s[4:5]
	v_lshl_add_u64 v[136:137], v[132:133], 0, v[128:129]
	v_lshl_add_u64 v[134:135], v[130:131], 0, v[128:129]
	v_add_u32_e32 v145, v139, v140
	ds_read_b128 v[148:151], v145
	v_add_u32_e32 v146, v139, v141
	ds_read_b128 v[152:155], v146 offset:16384
	ds_read_b128 v[156:159], v145 offset:4096
	ds_read_b128 v[160:163], v146 offset:20480
	s_cbranch_vccnz .LBB0_1508
	s_waitcnt vmcnt(8)
	v_add_co_u32_e32 v80, vcc, 0x10000, v136
	global_load_dwordx4 v[64:67], v[136:137], off offset:256
	global_load_dwordx4 v[72:75], v[134:135], off offset:256
	v_addc_co_u32_e32 v81, vcc, 0, v137, vcc
	v_add_co_u32_e32 v88, vcc, 0x10000, v134
	global_load_dwordx4 v[80:83], v[80:81], off offset:256
	s_nop 0
	v_addc_co_u32_e32 v89, vcc, 0, v135, vcc
	v_add_co_u32_e32 v96, vcc, 0x20000, v136
	global_load_dwordx4 v[88:91], v[88:89], off offset:256
	s_nop 0
	v_addc_co_u32_e32 v97, vcc, 0, v137, vcc
	v_add_co_u32_e32 v104, vcc, 0x20000, v134
	global_load_dwordx4 v[96:99], v[96:97], off offset:256
	s_nop 0
	v_addc_co_u32_e32 v105, vcc, 0, v135, vcc
	v_add_co_u32_e32 v112, vcc, 0x30000, v136
	global_load_dwordx4 v[104:107], v[104:105], off offset:256
	s_nop 0
	v_addc_co_u32_e32 v113, vcc, 0, v137, vcc
	v_add_co_u32_e32 v120, vcc, 0x30000, v134
	global_load_dwordx4 v[112:115], v[112:113], off offset:256
	s_nop 0
	v_addc_co_u32_e32 v121, vcc, 0, v135, vcc
	global_load_dwordx4 v[120:123], v[120:121], off offset:256

.Lg2w_w1:
	ds_write_b128 v138, v[68:71] offset:32768
	ds_write_b128 v138, v[76:79] offset:49152
	v_add_u32_e32 v147, v142, v140
	s_waitcnt lgkmcnt(2)
	v_mfma_f32_32x32x16_bf16 v[16:31], v[156:159], v[152:155], v[16:31]
	s_cmp_gt_u32 s16, 12
	v_mfma_f32_32x32x16_bf16 v[48:63], v[148:151], v[152:155], v[48:63]
	v_mfma_f32_32x32x16_bf16 v[32:47], v[148:151], v[160:163], v[32:47]
	ds_read_b128 v[150:153], v147
	v_add_u32_e32 v148, v142, v141
	v_add_u32_e32 v149, v143, v140
	v_mfma_f32_32x32x16_bf16 v[0:15], v[156:159], v[160:163], v[0:15]
	ds_read_b128 v[154:157], v148 offset:16384
	ds_read_b128 v[158:161], v147 offset:4096
	ds_read_b128 v[162:165], v148 offset:20480
	ds_write_b128 v138, v[84:87] offset:36864
	ds_write_b128 v138, v[92:95] offset:53248
	s_waitcnt lgkmcnt(2)
	v_mfma_f32_32x32x16_bf16 v[48:63], v[150:153], v[154:157], v[48:63]
	v_mfma_f32_32x32x16_bf16 v[32:47], v[150:153], v[162:165], v[32:47]
	v_add_u32_e32 v150, v143, v141
	v_add_u32_e32 v151, v144, v140
	v_mfma_f32_32x32x16_bf16 v[16:31], v[158:161], v[154:157], v[16:31]
	ds_read_b128 v[152:155], v149
	v_mfma_f32_32x32x16_bf16 v[0:15], v[158:161], v[162:165], v[0:15]
	ds_read_b128 v[156:159], v150 offset:16384
	ds_read_b128 v[160:163], v149 offset:4096
	ds_read_b128 v[170:173], v150 offset:20480
	ds_write_b128 v138, v[100:103] offset:40960
	ds_write_b128 v138, v[108:111] offset:57344
	s_waitcnt lgkmcnt(2)
	v_mfma_f32_32x32x16_bf16 v[48:63], v[152:155], v[156:159], v[48:63]
	v_mfma_f32_32x32x16_bf16 v[32:47], v[152:155], v[170:173], v[32:47]
	v_add_u32_e32 v152, v144, v141
	v_mfma_f32_32x32x16_bf16 v[16:31], v[160:163], v[156:159], v[16:31]
	ds_read_b128 v[154:157], v151
	v_mfma_f32_32x32x16_bf16 v[0:15], v[160:163], v[170:173], v[0:15]
	ds_read_b128 v[158:161], v152 offset:16384
	ds_read_b128 v[162:165], v151 offset:4096
	ds_read_b128 v[170:173], v152 offset:20480
	ds_write_b128 v138, v[116:119] offset:45056
	ds_write_b128 v138, v[124:127] offset:61440
	s_waitcnt lgkmcnt(2)
	v_mfma_f32_32x32x16_bf16 v[48:63], v[154:157], v[158:161], v[48:63]
	v_mfma_f32_32x32x16_bf16 v[32:47], v[154:157], v[170:173], v[32:47]
	v_mfma_f32_32x32x16_bf16 v[16:31], v[162:165], v[158:161], v[16:31]
	v_mfma_f32_32x32x16_bf16 v[0:15], v[162:165], v[170:173], v[0:15]
	s_waitcnt lgkmcnt(0)
	s_barrier
	ds_read_b128 v[154:157], v146 offset:49152
	ds_read_b128 v[158:161], v145 offset:36864
	ds_read_b128 v[162:165], v146 offset:53248
	s_cbranch_scc1 .LBB0_1510
	v_add_co_u32_e32 v84, vcc, 0x10000, v136
	global_load_dwordx4 v[68:71], v[136:137], off offset:384
	global_load_dwordx4 v[76:79], v[134:135], off offset:384
	v_addc_co_u32_e32 v85, vcc, 0, v137, vcc
	v_add_co_u32_e32 v92, vcc, 0x10000, v134
	global_load_dwordx4 v[84:87], v[84:85], off offset:384
	s_nop 0
	v_addc_co_u32_e32 v93, vcc, 0, v135, vcc
	v_add_co_u32_e32 v100, vcc, 0x20000, v136
	global_load_dwordx4 v[92:95], v[92:93], off offset:384
	s_nop 0
	v_addc_co_u32_e32 v101, vcc, 0, v137, vcc
	v_add_co_u32_e32 v108, vcc, 0x20000, v134
	global_load_dwordx4 v[100:103], v[100:101], off offset:384
	s_nop 0
	v_addc_co_u32_e32 v109, vcc, 0, v135, vcc
	v_add_co_u32_e32 v116, vcc, 0x30000, v136
	global_load_dwordx4 v[108:111], v[108:109], off offset:384
	s_nop 0
	v_addc_co_u32_e32 v117, vcc, 0, v137, vcc
	v_add_co_u32_e32 v124, vcc, 0x30000, v134
	global_load_dwordx4 v[116:119], v[116:117], off offset:384
	s_nop 0
	v_addc_co_u32_e32 v125, vcc, 0, v135, vcc
	global_load_dwordx4 v[124:127], v[124:125], off offset:384
.LBB0_1510:
	s_waitcnt vmcnt(8)
	ds_read_b128 v[134:137], v145 offset:32768
	ds_write_b128 v138, v[64:67]
	ds_write_b128 v138, v[72:75] offset:16384
	s_andn2_b64 vcc, exec, s[6:7]
	s_waitcnt lgkmcnt(2)
	v_mfma_f32_32x32x16_bf16 v[48:63], v[134:137], v[154:157], v[48:63]
	v_mfma_f32_32x32x16_bf16 v[32:47], v[134:137], v[162:165], v[32:47]
	v_mfma_f32_32x32x16_bf16 v[16:31], v[158:161], v[154:157], v[16:31]
	v_mfma_f32_32x32x16_bf16 v[0:15], v[158:161], v[162:165], v[0:15]
	ds_read_b128 v[134:137], v147 offset:32768
	ds_read_b128 v[154:157], v148 offset:49152
	ds_read_b128 v[158:161], v147 offset:36864
	ds_read_b128 v[162:165], v148 offset:53248
	ds_write_b128 v138, v[80:83] offset:4096
	ds_write_b128 v138, v[88:91] offset:20480
	s_waitcnt lgkmcnt(2)
	v_mfma_f32_32x32x16_bf16 v[48:63], v[134:137], v[154:157], v[48:63]
	v_mfma_f32_32x32x16_bf16 v[32:47], v[134:137], v[162:165], v[32:47]
	v_mfma_f32_32x32x16_bf16 v[16:31], v[158:161], v[154:157], v[16:31]
	v_mfma_f32_32x32x16_bf16 v[0:15], v[158:161], v[162:165], v[0:15]
	ds_read_b128 v[134:137], v149 offset:32768
	ds_read_b128 v[154:157], v150 offset:49152
	ds_read_b128 v[146:149], v149 offset:36864
	ds_read_b128 v[158:161], v150 offset:53248
	ds_write_b128 v138, v[96:99] offset:8192
	ds_write_b128 v138, v[104:107] offset:24576
	s_waitcnt lgkmcnt(2)
	v_mfma_f32_32x32x16_bf16 v[48:63], v[134:137], v[154:157], v[48:63]
	v_mfma_f32_32x32x16_bf16 v[32:47], v[134:137], v[158:161], v[32:47]
	v_mfma_f32_32x32x16_bf16 v[16:31], v[146:149], v[154:157], v[16:31]
	v_mfma_f32_32x32x16_bf16 v[0:15], v[146:149], v[158:161], v[0:15]
	ds_read_b128 v[134:137], v151 offset:32768
	ds_read_b128 v[146:149], v152 offset:49152
	ds_read_b128 v[154:157], v151 offset:36864
	ds_read_b128 v[150:153], v152 offset:53248
	ds_write_b128 v138, v[112:115] offset:12288
	ds_write_b128 v138, v[120:123] offset:28672
	s_waitcnt lgkmcnt(2)
	v_mfma_f32_32x32x16_bf16 v[48:63], v[134:137], v[146:149], v[48:63]
	v_mfma_f32_32x32x16_bf16 v[32:47], v[134:137], v[150:153], v[32:47]
	v_mfma_f32_32x32x16_bf16 v[16:31], v[154:157], v[146:149], v[16:31]
	v_mfma_f32_32x32x16_bf16 v[0:15], v[154:157], v[150:153], v[0:15]
	s_branch .LBB0_1505
